# v22 + early barrier arrivers issue an L2 write-back before polling
# baseline (speedup 1.0000x reference)
; DI unsigned xb_ld(unsigned* p)              { return __hip_atomic_load(p, __ATOMIC_RELAXED, __HIP_MEMORY_SCOPE_AGENT); }
; DI unsigned xb_add(unsigned* p, unsigned v) { return __hip_atomic_fetch_add(p, v, __ATOMIC_RELAXED, __HIP_MEMORY_SCOPE_AGENT); }
; #define XB_SPIN(cond, bar) do { unsigned _sp = 0; while (cond) { __builtin_amdgcn_s_sleep(1); \
;     if ((++_sp & 255u) == 0u) { if (xb_ld(&(bar)[XB_TMO])) break; if (_sp > XB_SPIN_CAP) { atomicAdd(&(bar)[XB_TMO], 1u); break; } } } } while (0)
; DI void xcd_barrier(unsigned* bar, volatile LAS unsigned* st, int wv) {
;     ...
;     const unsigned old = xb_add(&bar[XB_XSUB(x)], 1u);
;     const unsigned gen = old / nloc;
;     if (old + 1u == (gen + 1u) * nloc) {
;       __builtin_amdgcn_fence(__ATOMIC_RELEASE, "agent");
;       asm volatile("s_waitcnt vmcnt(0)" ::: "memory");
;       const unsigned og = xb_add(&bar[XB_TOP], 1u);
;       const unsigned tg = og / nx;
;       if (og + 1u == (tg + 1u) * nx) xb_add(&bar[XB_TOPGEN], 1u);
;       else XB_SPIN(xb_ld(&bar[XB_TOPGEN]) == tg, bar);
;       __builtin_amdgcn_fence(__ATOMIC_ACQUIRE, "agent");
;       xb_add(&bar[XB_XGEN(x)], 1u);
;       asm volatile("s_waitcnt vmcnt(0)" ::: "memory");
;     } else {
;       XB_SPIN(xb_ld(&bar[XB_XGEN(x)]) == gen, bar);
;       __builtin_amdgcn_fence(__ATOMIC_ACQUIRE, "agent");
;       asm volatile("s_waitcnt vmcnt(0)" ::: "memory");
.LBB0_26:
	s_or_b64 exec, exec, s[8:9]
	v_cvt_f32_u32_e32 v5, v3
	s_waitcnt vmcnt(0)
	v_readfirstlane_b32 s6, v4
	v_sub_u32_e32 v4, 0, v3
	v_rcp_iflag_f32_e32 v5, v5
	v_add_u32_e32 v6, s6, v0
	v_mul_f32_e32 v5, 0x4f7ffffe, v5
	v_cvt_u32_f32_e32 v5, v5
	v_mul_lo_u32 v0, v4, v5
	v_mul_hi_u32 v0, v5, v0
	v_add_u32_e32 v0, v5, v0
	v_mul_hi_u32 v0, v6, v0
	v_mul_lo_u32 v4, v0, v3
	v_sub_u32_e32 v4, v6, v4
	v_add_u32_e32 v5, 1, v0
	v_cmp_ge_u32_e32 vcc, v4, v3
	s_nop 1
	v_cndmask_b32_e32 v0, v0, v5, vcc
	v_sub_u32_e32 v5, v4, v3
	v_cndmask_b32_e32 v4, v4, v5, vcc
	v_add_u32_e32 v5, 1, v0
	v_cmp_ge_u32_e32 vcc, v4, v3
	v_add_u32_e32 v4, 1, v6
	s_nop 0
	v_cndmask_b32_e32 v0, v0, v5, vcc
	v_mul_lo_u32 v5, v3, v0
	v_add_u32_e32 v3, v5, v3
	v_cmp_ne_u32_e32 vcc, v4, v3
	s_and_saveexec_b64 s[6:7], vcc
	s_xor_b64 s[6:7], exec, s[6:7]
	s_cbranch_execz .LBB0_40
	buffer_wbl2 sc1
	s_waitcnt lgkmcnt(0)
	global_load_dword v2, v230, s[4:5] offset:1024 sc1
	s_add_u32 s10, s4, 0x2400
	s_addc_u32 s11, s5, 0
	s_waitcnt vmcnt(0)
	v_cmp_eq_u32_e32 vcc, v2, v0
	s_and_saveexec_b64 s[8:9], vcc
	s_cbranch_execz .LBB0_39
	s_mov_b32 s23, s19
	s_mov_b32 s22, 1
	s_mov_b64 s[12:13], 0
	s_branch .LBB0_30
